# cross- and window-attention epilogues: row-per-lane dwordx2 stores paired into dwordx4 via v_permlane32_swap
# speedup vs baseline: 1.0155x; 1.0041x over previous
; DEV void st4(bf16_t* p, f32x4 v) { u32x2 w; w.x = pk2(v[0], v[1]); w.y = pk2(v[2], v[3]); *(u32x2*)p = w; }
; template <int DQK, int DV, int NDP, int MODE, bool PF>
; DEV void attn_unit(unsigned char* lds, const bf16_t* Q, int ldq, const bf16_t* K, int ldk, const bf16_t* VT, int ldvt, bf16_t* O, int ldo,
;                    int kt0, int ntiles, int qpos0, const float* biasg, float sinkl2) {
;     ...
;     const float ltot = lrun + __shfl_xor(lrun, 32), inv = 1.f / ltot;
;     bf16_t* orow = O + (size_t)(qg * 32 + r32) * ldo + dp * DVW;
; #pragma unroll
;     for (int db = 0; db < NDB; ++db)
; #pragma unroll
;         for (int g4 = 0; g4 < 4; ++g4) { f32x4 w = {o[db][4 * g4] * inv, o[db][4 * g4 + 1] * inv, o[db][4 * g4 + 2] * inv, o[db][4 * g4 + 3] * inv}; st4(orow + db * 32 + 8 * g4 + 4 * hi, w); }
.LBB0_1271:
	v_and_b32_e32 v33, 64, v227
	v_xor_b32_e32 v32, 32, v227
	v_add_u32_e32 v33, 64, v33
	v_cmp_lt_i32_e32 vcc, v32, v33
	s_lshl_b64 s[4:5], s[8:9], 1
	s_add_u32 s6, s22, s4
	v_cndmask_b32_e32 v32, v227, v32, vcc
	v_lshlrev_b32_e32 v32, 2, v32
	ds_bpermute_b32 v32, v32, v91
	s_addc_u32 s7, s23, s5
	s_waitcnt lgkmcnt(0)
	v_add_f32_e32 v32, v91, v32
	v_div_scale_f32 v33, s[4:5], v32, v32, 1.0
	v_rcp_f32_e32 v34, v33
	s_lshl_b32 s4, s26, 1
	s_add_u32 s4, s6, s4
	s_addc_u32 s5, s7, 0
	v_fma_f32 v35, -v33, v34, 1.0
	v_fmac_f32_e32 v34, v35, v34
	v_div_scale_f32 v35, vcc, 1.0, v32, 1.0
	v_mul_f32_e32 v36, v35, v34
	v_fma_f32 v37, -v33, v36, v35
	v_fmac_f32_e32 v36, v37, v34
	v_fma_f32 v33, -v33, v36, v35
	v_div_fmas_f32 v33, v33, v34, v36
	v_div_fixup_f32 v34, v33, v32, 1.0
	v_lshl_add_u64 v[32:33], s[4:5], 0, v[88:89]
	v_mov_b32_e32 v91, v128
	v_lshl_add_u64 v[32:33], v[32:33], 0, v[90:91]
	v_lshl_add_u64 v[32:33], v[32:33], 0, v[90:91]
	v_mul_f32_e32 v16, v16, v34
	v_mul_f32_e32 v17, v17, v34
	v_mul_f32_e32 v18, v18, v34
	v_mul_f32_e32 v19, v19, v34
	v_mul_f32_e32 v20, v20, v34
	v_mul_f32_e32 v21, v21, v34
	v_mul_f32_e32 v22, v22, v34
	v_mul_f32_e32 v23, v23, v34
	v_cvt_pk_bf16_f32 v16, v16, v17
	v_cvt_pk_bf16_f32 v17, v18, v19
	v_cvt_pk_bf16_f32 v18, v20, v21
	v_cvt_pk_bf16_f32 v19, v22, v23
	s_nop 1
	v_permlane32_swap_b32_e32 v16, v18
	v_permlane32_swap_b32_e32 v17, v19
	flat_store_dwordx4 v[32:33], v[16:19]
	v_mul_f32_e32 v24, v24, v34
	v_mul_f32_e32 v25, v25, v34
	v_mul_f32_e32 v26, v26, v34
	v_mul_f32_e32 v27, v27, v34
	v_mul_f32_e32 v28, v28, v34
	v_mul_f32_e32 v29, v29, v34
	v_mul_f32_e32 v30, v30, v34
	v_mul_f32_e32 v31, v31, v34
	v_cvt_pk_bf16_f32 v24, v24, v25
	v_cvt_pk_bf16_f32 v25, v26, v27
	v_cvt_pk_bf16_f32 v26, v28, v29
	v_cvt_pk_bf16_f32 v27, v30, v31
	s_nop 1
	v_permlane32_swap_b32_e32 v24, v26
	v_permlane32_swap_b32_e32 v25, v27
	flat_store_dwordx4 v[32:33], v[24:27] offset:32
	v_mul_f32_e32 v0, v0, v34
	v_mul_f32_e32 v1, v1, v34
	v_mul_f32_e32 v2, v2, v34
	v_mul_f32_e32 v3, v3, v34
	v_mul_f32_e32 v4, v4, v34
	v_mul_f32_e32 v5, v5, v34
	v_mul_f32_e32 v6, v6, v34
	v_mul_f32_e32 v7, v7, v34
	v_cvt_pk_bf16_f32 v0, v0, v1
	v_cvt_pk_bf16_f32 v1, v2, v3
	v_cvt_pk_bf16_f32 v2, v4, v5
	v_cvt_pk_bf16_f32 v3, v6, v7
	s_nop 1
	v_permlane32_swap_b32_e32 v0, v2
	v_permlane32_swap_b32_e32 v1, v3
	flat_store_dwordx4 v[32:33], v[0:3] offset:64
	v_mul_f32_e32 v8, v8, v34
	v_mul_f32_e32 v9, v9, v34
	v_mul_f32_e32 v10, v10, v34
	v_mul_f32_e32 v11, v11, v34
	v_mul_f32_e32 v12, v12, v34
	v_mul_f32_e32 v13, v13, v34
	v_mul_f32_e32 v14, v14, v34
	v_mul_f32_e32 v15, v15, v34
	v_cvt_pk_bf16_f32 v8, v8, v9
	v_cvt_pk_bf16_f32 v9, v10, v11
	v_cvt_pk_bf16_f32 v10, v12, v13
	v_cvt_pk_bf16_f32 v11, v14, v15
	s_nop 1
	v_permlane32_swap_b32_e32 v8, v10
	v_permlane32_swap_b32_e32 v9, v11
	flat_store_dwordx4 v[32:33], v[8:11] offset:96
	v_readlane_b32 s4, v254, 0
	s_nop 1
	s_add_i32 s25, s25, s4
	s_cmpk_gt_i32 s25, 0x3ff
	v_readlane_b32 s5, v254, 1
	s_cbranch_scc1 .LBB0_1346

; template <int DQK, int DV, int NDP, int MODE, bool PF>
; DEV void attn_unit(unsigned char* lds, const bf16_t* Q, int ldq, const bf16_t* K, int ldk, const bf16_t* VT, int ldvt, bf16_t* O, int ldo,
;                    int kt0, int ntiles, int qpos0, const float* biasg, float sinkl2) {
;     ...
;     for (int ti = 0; ti < ntiles; ++ti) {
;         const int kt = kt0 + ti * 64;
;         __syncthreads();
;         if (!PF) ATT_GLOAD(kt);
;         ATT_LSTORE();
;         if (MODE == 1 && ti == 0) { for (int i = tid; i < 257; i += 512) bt[i] = biasg[i]; }
;         __syncthreads();
;         if (PF && ti + 1 < ntiles) ATT_GLOAD(kt + 64);
;         bool skip = false;
;         if (MODE == 1) { const int qlo = qpos0 + qg * 32; skip = (kt > qlo + 31 + 128) || (kt + 63 < qlo - 128); }
;         if (!skip) {
;             f32x16 p0, p1;
; #pragma unroll
;             for (int r = 0; r < 16; ++r) { p0[r] = 0.f; p1[r] = 0.f; }
; #pragma unroll
;             for (int d0 = 0; d0 < ND0; ++d0) {
;                 const bf16x8 k0 = *(const bf16x8*)(Kt + krow * KP + d0 * 16 + hi * 8), k1 = *(const bf16x8*)(Kt + (32 + krow) * KP + d0 * 16 + hi * 8);
;                 p0 = __builtin_amdgcn_mfma_f32_32x32x16_bf16(k0, qf[d0], p0, 0, 0, 0);
;                 p1 = __builtin_amdgcn_mfma_f32_32x32x16_bf16(k1, qf[d0], p1, 0, 0, 0);
;             }
.LBB0_1709:
	v_lshl_add_u64 v[64:65], s[8:9], 0, v[178:179]
	v_lshl_add_u64 v[68:69], s[8:9], 0, v[176:177]
	v_lshl_add_u64 v[72:73], s[8:9], 0, v[174:175]
	v_lshl_add_u64 v[76:77], s[8:9], 0, v[172:173]
	v_lshl_add_u64 v[80:81], s[8:9], 0, v[170:171]
	v_lshl_add_u64 v[84:85], s[8:9], 0, v[168:169]
	v_lshl_add_u64 v[88:89], s[8:9], 0, v[166:167]
	v_lshl_add_u64 v[92:93], s[8:9], 0, v[164:165]
	s_waitcnt lgkmcnt(0)
	s_barrier
	flat_load_dwordx4 v[64:67], v[64:65]
	s_nop 0
	flat_load_dwordx4 v[68:71], v[68:69]
	s_nop 0
	flat_load_dwordx4 v[72:75], v[72:73]
	s_nop 0
	flat_load_dwordx4 v[76:79], v[76:77]
	s_nop 0
	flat_load_dwordx4 v[80:83], v[80:81]
	s_nop 0
	flat_load_dwordx4 v[84:87], v[84:85]
	s_nop 0
	flat_load_dwordx4 v[88:91], v[88:89]
	s_nop 0
	flat_load_dwordx4 v[92:95], v[92:93]
	s_add_i32 s20, s20, -1
	v_lshl_add_u64 v[164:165], v[164:165], 0, s[82:83]
	v_lshl_add_u64 v[166:167], v[166:167], 0, s[82:83]
	v_lshl_add_u64 v[168:169], v[168:169], 0, s[82:83]
	v_lshl_add_u64 v[170:171], v[170:171], 0, s[82:83]
	v_lshl_add_u64 v[172:173], v[172:173], 0, s[78:79]
	v_lshl_add_u64 v[174:175], v[174:175], 0, s[78:79]
	v_lshl_add_u64 v[176:177], v[176:177], 0, s[78:79]
	v_lshl_add_u64 v[178:179], v[178:179], 0, s[78:79]
	s_cmp_lg_u32 s20, 0
	s_waitcnt vmcnt(0) lgkmcnt(0)
	ds_write_b128 v192, v[64:67]
	ds_write_b128 v193, v[68:71]
	ds_write_b128 v194, v[72:75]
	ds_write_b128 v195, v[76:79]
	ds_write_b128 v196, v[80:83] offset:33792
	ds_write_b128 v197, v[84:87] offset:33792
	ds_write_b128 v198, v[88:91] offset:33792
	ds_write_b128 v199, v[92:95] offset:33792
	s_waitcnt lgkmcnt(0)
	s_barrier
	ds_read_b128 v[64:67], v191
	ds_read_b128 v[180:183], v191 offset:32
	s_waitcnt lgkmcnt(1)
	v_mfma_f32_32x32x16_bf16 v[64:79], v[64:67], v[96:99], 0
	ds_read_b128 v[80:83], v191 offset:16896
	ds_read_b128 v[184:187], v191 offset:16928
	s_waitcnt lgkmcnt(1)
	v_mfma_f32_32x32x16_bf16 v[80:95], v[80:83], v[96:99], 0
	v_mfma_f32_32x32x16_bf16 v[64:79], v[180:183], v[100:103], v[64:79]
	s_waitcnt lgkmcnt(0)
	v_mfma_f32_32x32x16_bf16 v[80:95], v[184:187], v[100:103], v[80:95]
	ds_read_b128 v[180:183], v191 offset:64
	ds_read_b128 v[184:187], v191 offset:96
	s_waitcnt lgkmcnt(1)
	v_mfma_f32_32x32x16_bf16 v[64:79], v[180:183], v[104:107], v[64:79]
	ds_read_b128 v[180:183], v191 offset:16960
	ds_read_b128 v[200:203], v191 offset:16992
	s_waitcnt lgkmcnt(1)
	v_mfma_f32_32x32x16_bf16 v[80:95], v[180:183], v[104:107], v[80:95]
	v_mfma_f32_32x32x16_bf16 v[64:79], v[184:187], v[108:111], v[64:79]
	ds_read_b128 v[180:183], v191 offset:128
	ds_read_b128 v[184:187], v191 offset:160
	s_waitcnt lgkmcnt(2)
	v_mfma_f32_32x32x16_bf16 v[80:95], v[200:203], v[108:111], v[80:95]
	s_waitcnt lgkmcnt(1)
	v_mfma_f32_32x32x16_bf16 v[64:79], v[180:183], v[112:115], v[64:79]
	ds_read_b128 v[180:183], v191 offset:17024
	ds_read_b128 v[200:203], v191 offset:17056
	s_waitcnt lgkmcnt(1)
	v_mfma_f32_32x32x16_bf16 v[80:95], v[180:183], v[112:115], v[80:95]
	v_mfma_f32_32x32x16_bf16 v[64:79], v[184:187], v[116:119], v[64:79]
	ds_read_b128 v[180:183], v191 offset:192
	ds_read_b128 v[184:187], v191 offset:224
	s_waitcnt lgkmcnt(2)
	v_mfma_f32_32x32x16_bf16 v[80:95], v[200:203], v[116:119], v[80:95]
	s_waitcnt lgkmcnt(1)
	v_mfma_f32_32x32x16_bf16 v[64:79], v[180:183], v[120:123], v[64:79]
	ds_read_b128 v[180:183], v191 offset:17088
	ds_read_b128 v[200:203], v191 offset:17120
	s_waitcnt lgkmcnt(1)
	v_mfma_f32_32x32x16_bf16 v[80:95], v[180:183], v[120:123], v[80:95]
	v_mfma_f32_32x32x16_bf16 v[64:79], v[184:187], v[124:127], v[64:79]
	ds_read_b128 v[180:183], v191 offset:256
	ds_read_b128 v[184:187], v191 offset:288
	s_waitcnt lgkmcnt(2)
	v_mfma_f32_32x32x16_bf16 v[80:95], v[200:203], v[124:127], v[80:95]
	s_waitcnt lgkmcnt(1)
	v_mfma_f32_32x32x16_bf16 v[64:79], v[180:183], v[130:133], v[64:79]
	ds_read_b128 v[180:183], v191 offset:17152
	ds_read_b128 v[200:203], v191 offset:17184
	s_waitcnt lgkmcnt(1)
	v_mfma_f32_32x32x16_bf16 v[80:95], v[180:183], v[130:133], v[80:95]
	v_mfma_f32_32x32x16_bf16 v[64:79], v[184:187], v[134:137], v[64:79]
	ds_read_b128 v[180:183], v191 offset:320
	ds_read_b128 v[184:187], v191 offset:352
	s_waitcnt lgkmcnt(2)
	v_mfma_f32_32x32x16_bf16 v[80:95], v[200:203], v[134:137], v[80:95]
	s_waitcnt lgkmcnt(1)
	v_mfma_f32_32x32x16_bf16 v[64:79], v[180:183], v[138:141], v[64:79]
	ds_read_b128 v[180:183], v191 offset:17216
	ds_read_b128 v[200:203], v191 offset:17248
	s_waitcnt lgkmcnt(1)
	v_mfma_f32_32x32x16_bf16 v[80:95], v[180:183], v[138:141], v[80:95]
	v_mfma_f32_32x32x16_bf16 v[64:79], v[184:187], v[142:145], v[64:79]
	ds_read_b128 v[180:183], v191 offset:384
	ds_read_b128 v[184:187], v191 offset:416
	s_waitcnt lgkmcnt(2)
	v_mfma_f32_32x32x16_bf16 v[80:95], v[200:203], v[142:145], v[80:95]
	s_waitcnt lgkmcnt(1)
	v_mfma_f32_32x32x16_bf16 v[64:79], v[180:183], v[146:149], v[64:79]
	ds_read_b128 v[180:183], v191 offset:17280
	ds_read_b128 v[200:203], v191 offset:17312
	s_waitcnt lgkmcnt(1)
	v_mfma_f32_32x32x16_bf16 v[80:95], v[180:183], v[146:149], v[80:95]
	v_mfma_f32_32x32x16_bf16 v[64:79], v[184:187], v[150:153], v[64:79]
	ds_read_b128 v[180:183], v191 offset:448
	ds_read_b128 v[184:187], v191 offset:480
	s_waitcnt lgkmcnt(2)
	v_mfma_f32_32x32x16_bf16 v[80:95], v[200:203], v[150:153], v[80:95]
	s_waitcnt lgkmcnt(1)
	v_mfma_f32_32x32x16_bf16 v[64:79], v[180:183], v[154:157], v[64:79]
	ds_read_b128 v[180:183], v191 offset:17344
	ds_read_b128 v[200:203], v191 offset:17376
	s_waitcnt lgkmcnt(1)
	v_mfma_f32_32x32x16_bf16 v[80:95], v[180:183], v[154:157], v[80:95]
	v_mfma_f32_32x32x16_bf16 v[64:79], v[184:187], v[158:161], v[64:79]
	s_waitcnt lgkmcnt(0)
; DEV unsigned pk2(float lo, float hi) { return pg8::cvt_pk_bf16(lo, hi); }
; template <int DQK, int DV, int NDP, int MODE, bool PF>
; DEV void attn_unit(unsigned char* lds, const bf16_t* Q, int ldq, const bf16_t* K, int ldk, const bf16_t* VT, int ldvt, bf16_t* O, int ldo,
;                    int kt0, int ntiles, int qpos0, const float* biasg, float sinkl2) {
;     ...
;             float mx = fmaxf(p0[0], p1[0]);
; #pragma unroll
;             for (int r = 1; r < 16; ++r) mx = fmaxf(mx, fmaxf(p0[r], p1[r]));
;             mx = fmaxf(mx, __shfl_xor(mx, 32));
;             const float mnew = fmaxf(mrun, mx), alpha = __builtin_amdgcn_exp2f(mrun - mnew); mrun = mnew;
;             float rsum = 0.f;
; #pragma unroll
;             for (int r = 0; r < 16; ++r) { p0[r] = __builtin_amdgcn_exp2f(p0[r] - mnew); p1[r] = __builtin_amdgcn_exp2f(p1[r] - mnew); rsum += p0[r] + p1[r]; }
;             lrun = lrun * alpha + rsum;
; #pragma unroll
;             for (int i = 0; i < NDB; ++i)
; #pragma unroll
;                 for (int r = 0; r < 16; ++r) o[i][r] *= alpha;
;             bf16x8 pb[4];
; #pragma unroll
;             for (int ks = 0; ks < 4; ++ks) { u32x4 w;
;                 if (ks < 2) { w.x = pk2(p0[8 * ks + 0], p0[8 * ks + 1]); w.y = pk2(p0[8 * ks + 2], p0[8 * ks + 3]); w.z = pk2(p0[8 * ks + 4], p0[8 * ks + 5]); w.w = pk2(p0[8 * ks + 6], p0[8 * ks + 7]); }
;                 else { const int k2 = ks - 2; w.x = pk2(p1[8 * k2 + 0], p1[8 * k2 + 1]); w.y = pk2(p1[8 * k2 + 2], p1[8 * k2 + 3]); w.z = pk2(p1[8 * k2 + 4], p1[8 * k2 + 5]); w.w = pk2(p1[8 * k2 + 6], p1[8 * k2 + 7]); }
;                 pb[ks] = __builtin_bit_cast(bf16x8, w); }
; #pragma unroll
;             for (int db = 0; db < NDB; ++db)
; #pragma unroll
;                 for (int ks = 0; ks < 4; ++ks) {
;                     const bf16x8 vf = *(const bf16x8*)(Vt + (dp * DVW + db * 32 + r32) * VP + ks * 16 + hi * 8);
;                     o[db] = __builtin_amdgcn_mfma_f32_32x32x16_bf16(vf, pb[ks], o[db], 0, 0, 0);
	v_mfma_f32_32x32x16_bf16 v[80:95], v[200:203], v[158:161], v[80:95]
	s_nop 9
	v_max_f32_e32 v181, v65, v65
	v_max_f32_e32 v183, v66, v66
	v_max_f32_e32 v185, v67, v67
	v_max_f32_e32 v187, v68, v68
	v_max_f32_e32 v189, v69, v69
	v_max_f32_e32 v201, v70, v70
	v_max_f32_e32 v203, v71, v71
	v_max_f32_e32 v180, v81, v81
	v_max_f32_e32 v182, v82, v82
	v_max_f32_e32 v184, v83, v83
	v_max_f32_e32 v180, v181, v180
	v_max_f32_e32 v186, v84, v84
	v_max_f32_e32 v188, v85, v85
	v_max_f32_e32 v181, v183, v182
	v_max_f32_e32 v182, v185, v184
	v_max3_f32 v180, v64, v80, v180
	v_max_f32_e32 v200, v86, v86
	v_max_f32_e32 v202, v87, v87
	v_max_f32_e32 v183, v187, v186
	v_max_f32_e32 v184, v189, v188
	v_max3_f32 v180, v180, v181, v182
	v_max_f32_e32 v204, v88, v88
	v_max_f32_e32 v205, v72, v72
	v_max_f32_e32 v207, v89, v89
	v_max_f32_e32 v208, v73, v73
	v_max_f32_e32 v185, v201, v200
	v_max_f32_e32 v186, v203, v202
	v_max3_f32 v180, v180, v183, v184
	v_max_f32_e32 v209, v90, v90
	v_max_f32_e32 v210, v74, v74
	v_max_f32_e32 v211, v91, v91
	v_max_f32_e32 v212, v75, v75
	v_max_f32_e32 v187, v205, v204
	v_max_f32_e32 v188, v208, v207
	v_max3_f32 v180, v180, v185, v186
	v_max_f32_e32 v213, v92, v92
	v_max_f32_e32 v214, v76, v76
	v_max_f32_e32 v215, v93, v93
	v_max_f32_e32 v218, v77, v77
	v_max_f32_e32 v189, v210, v209
	v_max_f32_e32 v200, v212, v211
	v_max3_f32 v180, v180, v187, v188
	v_max_f32_e32 v219, v94, v94
	v_max_f32_e32 v220, v78, v78
	v_max_f32_e32 v221, v95, v95
	v_max_f32_e32 v222, v79, v79
	v_max_f32_e32 v201, v214, v213
	v_max_f32_e32 v202, v218, v215
	v_max3_f32 v180, v180, v189, v200
	v_max_f32_e32 v203, v220, v219
	v_max_f32_e32 v204, v222, v221
	v_max3_f32 v180, v180, v201, v202
	v_max3_f32 v180, v180, v203, v204
	ds_bpermute_b32 v181, v190, v180
	v_mov_b32_e32 v215, v216
	s_waitcnt lgkmcnt(0)
	v_max3_f32 v207, v217, v180, v181
	v_sub_f32_e32 v180, v217, v207
	v_sub_f32_e32 v64, v64, v207
	v_sub_f32_e32 v181, v80, v207
	v_sub_f32_e32 v65, v65, v207
	v_sub_f32_e32 v182, v81, v207
	v_sub_f32_e32 v66, v66, v207
	v_sub_f32_e32 v82, v82, v207
	v_sub_f32_e32 v67, v67, v207
	v_sub_f32_e32 v83, v83, v207
	v_sub_f32_e32 v68, v68, v207
	v_sub_f32_e32 v84, v84, v207
	v_sub_f32_e32 v69, v69, v207
	v_sub_f32_e32 v183, v85, v207
	v_sub_f32_e32 v70, v70, v207
	v_sub_f32_e32 v86, v86, v207
	v_sub_f32_e32 v71, v71, v207
	v_sub_f32_e32 v184, v87, v207
	v_sub_f32_e32 v72, v72, v207
	v_sub_f32_e32 v185, v88, v207
	v_sub_f32_e32 v73, v73, v207
	v_sub_f32_e32 v186, v89, v207
	v_sub_f32_e32 v74, v74, v207
	v_sub_f32_e32 v187, v90, v207
	v_sub_f32_e32 v75, v75, v207
	v_sub_f32_e32 v188, v91, v207
	v_sub_f32_e32 v76, v76, v207
	v_sub_f32_e32 v189, v92, v207
	v_sub_f32_e32 v77, v77, v207
	v_sub_f32_e32 v200, v93, v207
	v_sub_f32_e32 v78, v78, v207
	v_sub_f32_e32 v201, v94, v207
	v_sub_f32_e32 v79, v79, v207
	v_sub_f32_e32 v202, v95, v207
	v_exp_f32_e32 v80, v180
	v_exp_f32_e32 v81, v64
	v_exp_f32_e32 v209, v181
	v_exp_f32_e32 v208, v65
	v_exp_f32_e32 v211, v182
	v_exp_f32_e32 v210, v66
	v_exp_f32_e32 v213, v82
	v_exp_f32_e32 v212, v67
	v_exp_f32_e32 v214, v83
	v_exp_f32_e32 v83, v68
	v_exp_f32_e32 v85, v84
	v_exp_f32_e32 v82, v69
	v_exp_f32_e32 v84, v183
	v_exp_f32_e32 v87, v70
	v_exp_f32_e32 v89, v86
	v_exp_f32_e32 v86, v71
	v_exp_f32_e32 v88, v184
	v_exp_f32_e32 v91, v72
	v_exp_f32_e32 v93, v185
	v_exp_f32_e32 v90, v73
	v_exp_f32_e32 v92, v186
	v_exp_f32_e32 v95, v74
	v_exp_f32_e32 v181, v187
	v_exp_f32_e32 v94, v75
	v_exp_f32_e32 v180, v188
	v_exp_f32_e32 v183, v76
	v_exp_f32_e32 v185, v189
	v_exp_f32_e32 v182, v77
	v_exp_f32_e32 v184, v200
	v_exp_f32_e32 v187, v78
	v_exp_f32_e32 v189, v201
	v_exp_f32_e32 v186, v79
	v_exp_f32_e32 v188, v202
	v_cvt_pk_bf16_f32 v200, v81, v208
	v_cvt_pk_bf16_f32 v201, v210, v212
	v_cvt_pk_bf16_f32 v202, v83, v82
	v_cvt_pk_bf16_f32 v203, v87, v86
	v_cvt_pk_bf16_f32 v72, v91, v90
	v_cvt_pk_bf16_f32 v73, v95, v94
	v_cvt_pk_bf16_f32 v74, v183, v182
	v_cvt_pk_bf16_f32 v75, v187, v186
	v_cvt_pk_bf16_f32 v68, v209, v211
	v_cvt_pk_bf16_f32 v69, v213, v214
	v_cvt_pk_bf16_f32 v70, v85, v84
	v_cvt_pk_bf16_f32 v71, v89, v88
	v_cvt_pk_bf16_f32 v64, v93, v92
	v_cvt_pk_bf16_f32 v65, v181, v180
	v_cvt_pk_bf16_f32 v66, v185, v184
	v_cvt_pk_bf16_f32 v67, v189, v188
	ds_read_b128 v[76:79], v206 offset:33792
	ds_read_b128 v[218:221], v206 offset:33824
	ds_read_b128 v[230:233], v206 offset:38400
	v_pk_mul_f32 v[62:63], v[62:63], v[80:81] op_sel_hi:[1,0]
	v_pk_mul_f32 v[60:61], v[60:61], v[80:81] op_sel_hi:[1,0]
	v_pk_mul_f32 v[58:59], v[58:59], v[80:81] op_sel_hi:[1,0]
	v_pk_mul_f32 v[56:57], v[56:57], v[80:81] op_sel_hi:[1,0]
	v_pk_mul_f32 v[54:55], v[54:55], v[80:81] op_sel_hi:[1,0]
	v_pk_mul_f32 v[52:53], v[52:53], v[80:81] op_sel_hi:[1,0]
	v_pk_mul_f32 v[50:51], v[50:51], v[80:81] op_sel_hi:[1,0]
	v_pk_mul_f32 v[48:49], v[48:49], v[80:81] op_sel_hi:[1,0]
	v_pk_mul_f32 v[46:47], v[46:47], v[80:81] op_sel_hi:[1,0]
	v_pk_mul_f32 v[44:45], v[44:45], v[80:81] op_sel_hi:[1,0]
	v_pk_mul_f32 v[42:43], v[42:43], v[80:81] op_sel_hi:[1,0]
	v_pk_mul_f32 v[40:41], v[40:41], v[80:81] op_sel_hi:[1,0]
	v_pk_mul_f32 v[38:39], v[38:39], v[80:81] op_sel_hi:[1,0]
	v_pk_mul_f32 v[36:37], v[36:37], v[80:81] op_sel_hi:[1,0]
	v_pk_mul_f32 v[34:35], v[34:35], v[80:81] op_sel_hi:[1,0]
	v_pk_mul_f32 v[32:33], v[32:33], v[80:81] op_sel_hi:[1,0]
	s_waitcnt lgkmcnt(2)
	v_mfma_f32_32x32x16_bf16 v[48:63], v[76:79], v[200:203], v[48:63]
	ds_read_b128 v[234:237], v206 offset:38432
	ds_read_b128 v[76:79], v206 offset:43008
	v_mul_f32_e64 v30, v30, v80
	v_mul_f32_e64 v31, v31, v80
	v_mul_f32_e64 v28, v28, v80
	v_mul_f32_e64 v29, v29, v80
	v_pk_mul_f32 v[26:27], v[26:27], v[80:81] op_sel_hi:[1,0]
	v_pk_mul_f32 v[24:25], v[24:25], v[80:81] op_sel_hi:[1,0]
	v_pk_mul_f32 v[22:23], v[22:23], v[80:81] op_sel_hi:[1,0]
	v_pk_mul_f32 v[20:21], v[20:21], v[80:81] op_sel_hi:[1,0]
	s_waitcnt lgkmcnt(2)
; DEV unsigned pk2(float lo, float hi) { return pg8::cvt_pk_bf16(lo, hi); }
; template <int DQK, int DV, int NDP, int MODE, bool PF>
; DEV void attn_unit(unsigned char* lds, const bf16_t* Q, int ldq, const bf16_t* K, int ldk, const bf16_t* VT, int ldvt, bf16_t* O, int ldo,
;                    int kt0, int ntiles, int qpos0, const float* biasg, float sinkl2) {
;     ...
;             for (int r = 0; r < 16; ++r) { p0[r] = __builtin_amdgcn_exp2f(p0[r] - mnew); p1[r] = __builtin_amdgcn_exp2f(p1[r] - mnew); rsum += p0[r] + p1[r]; }
;             lrun = lrun * alpha + rsum;
; #pragma unroll
;             for (int i = 0; i < NDB; ++i)
; #pragma unroll
;                 for (int r = 0; r < 16; ++r) o[i][r] *= alpha;
;             bf16x8 pb[4];
; #pragma unroll
;             for (int ks = 0; ks < 4; ++ks) { u32x4 w;
;                 if (ks < 2) { w.x = pk2(p0[8 * ks + 0], p0[8 * ks + 1]); w.y = pk2(p0[8 * ks + 2], p0[8 * ks + 3]); w.z = pk2(p0[8 * ks + 4], p0[8 * ks + 5]); w.w = pk2(p0[8 * ks + 6], p0[8 * ks + 7]); }
;                 else { const int k2 = ks - 2; w.x = pk2(p1[8 * k2 + 0], p1[8 * k2 + 1]); w.y = pk2(p1[8 * k2 + 2], p1[8 * k2 + 3]); w.z = pk2(p1[8 * k2 + 4], p1[8 * k2 + 5]); w.w = pk2(p1[8 * k2 + 6], p1[8 * k2 + 7]); }
;                 pb[ks] = __builtin_bit_cast(bf16x8, w); }
; #pragma unroll
;             for (int db = 0; db < NDB; ++db)
; #pragma unroll
;                 for (int ks = 0; ks < 4; ++ks) {
;                     const bf16x8 vf = *(const bf16x8*)(Vt + (dp * DVW + db * 32 + r32) * VP + ks * 16 + hi * 8);
;                     o[db] = __builtin_amdgcn_mfma_f32_32x32x16_bf16(vf, pb[ks], o[db], 0, 0, 0);
;                 }
	v_mfma_f32_32x32x16_bf16 v[32:47], v[230:233], v[200:203], v[32:47]
	ds_read_b128 v[230:233], v206 offset:43040
	ds_read_b128 v[238:241], v206 offset:47616
	v_mul_f32_e64 v18, v18, v80
	v_mul_f32_e64 v19, v19, v80
	v_mul_f32_e64 v16, v16, v80
	v_mul_f32_e64 v17, v17, v80
	v_pk_mul_f32 v[14:15], v[14:15], v[80:81] op_sel_hi:[1,0]
	v_pk_mul_f32 v[12:13], v[12:13], v[80:81] op_sel_hi:[1,0]
	v_pk_mul_f32 v[10:11], v[10:11], v[80:81] op_sel_hi:[1,0]
	v_pk_mul_f32 v[8:9], v[8:9], v[80:81] op_sel_hi:[1,0]
	s_waitcnt lgkmcnt(2)
	v_mfma_f32_32x32x16_bf16 v[16:31], v[76:79], v[200:203], v[16:31]
	v_mul_f32_e64 v6, v6, v80
	v_mul_f32_e64 v7, v7, v80
	v_mul_f32_e64 v4, v4, v80
	v_mul_f32_e64 v5, v5, v80
	v_mul_f32_e64 v2, v2, v80
	v_mul_f32_e64 v3, v3, v80
	v_pk_mul_f32 v[0:1], v[0:1], v[80:81] op_sel_hi:[1,0]
	ds_read_b128 v[76:79], v206 offset:47648
	v_add_f32_e32 v81, v81, v209
	v_add_f32_e32 v204, v208, v211
	s_waitcnt lgkmcnt(1)
	v_mfma_f32_32x32x16_bf16 v[0:15], v[238:241], v[200:203], v[0:15]
	v_add_f32_e32 v81, 0, v81
	v_add_f32_e32 v205, v210, v213
	v_add_f32_e32 v81, v204, v81
	v_mov_b32_e32 v217, v207
	v_add_f32_e32 v207, v212, v214
	v_add_f32_e32 v81, v205, v81
	v_add_f32_e32 v81, v207, v81
	v_mfma_f32_32x32x16_bf16 v[48:63], v[218:221], v[72:75], v[48:63]
	v_mfma_f32_32x32x16_bf16 v[32:47], v[234:237], v[72:75], v[32:47]
	v_mfma_f32_32x32x16_bf16 v[16:31], v[230:233], v[72:75], v[16:31]
	s_waitcnt lgkmcnt(0)
	v_mfma_f32_32x32x16_bf16 v[0:15], v[76:79], v[72:75], v[0:15]
	ds_read_b128 v[72:75], v206 offset:33856
	ds_read_b128 v[76:79], v206 offset:33888
	s_waitcnt lgkmcnt(1)
	v_mfma_f32_32x32x16_bf16 v[48:63], v[72:75], v[68:71], v[48:63]
	ds_read_b128 v[72:75], v206 offset:38464
	ds_read_b128 v[200:203], v206 offset:38496
	s_waitcnt lgkmcnt(1)
	v_mfma_f32_32x32x16_bf16 v[32:47], v[72:75], v[68:71], v[32:47]
	ds_read_b128 v[72:75], v206 offset:43072
	ds_read_b128 v[218:221], v206 offset:43104
	s_waitcnt lgkmcnt(1)
	v_mfma_f32_32x32x16_bf16 v[16:31], v[72:75], v[68:71], v[16:31]
	ds_read_b128 v[72:75], v206 offset:47680
	ds_read_b128 v[230:233], v206 offset:47712
	s_waitcnt lgkmcnt(1)
	v_mfma_f32_32x32x16_bf16 v[0:15], v[72:75], v[68:71], v[0:15]
	v_add_f32_e64 v68, v82, v84
	v_add_f32_e64 v69, v83, v85
	v_add_f32_e64 v70, v86, v88
	v_add_f32_e64 v71, v87, v89
	v_add_f32_e32 v69, v69, v81
	v_add_f32_e32 v68, v68, v69
	v_add_f32_e32 v68, v71, v68
	v_pk_add_f32 v[72:73], v[90:91], v[92:93]
	v_add_f32_e32 v68, v70, v68
	v_add_f32_e32 v68, v73, v68
	v_mfma_f32_32x32x16_bf16 v[48:63], v[76:79], v[64:67], v[48:63]
	v_add_f32_e64 v74, v94, v180
	v_add_f32_e64 v75, v95, v181
	v_add_f32_e32 v68, v72, v68
	v_add_f32_e64 v76, v182, v184
	v_add_f32_e64 v77, v183, v185
	v_pk_add_f32 v[78:79], v[186:187], v[188:189]
	v_mfma_f32_32x32x16_bf16 v[32:47], v[200:203], v[64:67], v[32:47]
	v_mfma_f32_32x32x16_bf16 v[16:31], v[218:221], v[64:67], v[16:31]
	s_waitcnt lgkmcnt(0)
	v_mfma_f32_32x32x16_bf16 v[0:15], v[230:233], v[64:67], v[0:15]
	v_add_f32_e32 v64, v75, v68
	v_add_f32_e32 v64, v74, v64
	v_add_f32_e32 v64, v77, v64
	v_add_f32_e32 v64, v76, v64
	v_add_f32_e32 v64, v79, v64
	v_add_f32_e32 v216, v78, v64
	v_fmac_f32_e32 v216, v215, v80
	s_cbranch_scc1 .LBB0_1709
; DEV void st4(bf16_t* p, f32x4 v) { u32x2 w; w.x = pk2(v[0], v[1]); w.y = pk2(v[2], v[3]); *(u32x2*)p = w; }
; template <int DQK, int DV, int NDP, int MODE, bool PF>
; DEV void attn_unit(unsigned char* lds, const bf16_t* Q, int ldq, const bf16_t* K, int ldk, const bf16_t* VT, int ldvt, bf16_t* O, int ldo,
;                    int kt0, int ntiles, int qpos0, const float* biasg, float sinkl2) {
;     ...
;     const float ltot = lrun + __shfl_xor(lrun, 32), inv = 1.f / ltot;
;     bf16_t* orow = O + (size_t)(qg * 32 + r32) * ldo + dp * DVW;
; #pragma unroll
;     for (int db = 0; db < NDB; ++db)
; #pragma unroll
;         for (int g4 = 0; g4 < 4; ++g4) { f32x4 w = {o[db][4 * g4] * inv, o[db][4 * g4 + 1] * inv, o[db][4 * g4 + 2] * inv, o[db][4 * g4 + 3] * inv}; st4(orow + db * 32 + 8 * g4 + 4 * hi, w); }
	ds_bpermute_b32 v64, v190, v216
	s_lshl_b64 s[6:7], s[6:7], 1
	s_add_u32 s12, s16, s6
	s_addc_u32 s13, s17, s7
	s_waitcnt lgkmcnt(0)
	v_add_f32_e32 v64, v216, v64
	v_div_scale_f32 v65, s[6:7], v64, v64, 1.0
	v_rcp_f32_e32 v66, v65
	s_lshl_b32 s6, s11, 1
	s_add_u32 s6, s12, s6
	s_addc_u32 s7, s13, 0
	v_fma_f32 v67, -v65, v66, 1.0
	v_fmac_f32_e32 v66, v67, v66
	v_div_scale_f32 v67, vcc, 1.0, v64, 1.0
	v_mul_f32_e32 v68, v67, v66
	v_fma_f32 v69, -v65, v68, v67
	v_fmac_f32_e32 v68, v69, v66
	v_fma_f32 v65, -v65, v68, v67
	v_div_fmas_f32 v65, v65, v66, v68
	v_div_fixup_f32 v68, v65, v64, 1.0
	v_lshl_add_u64 v[64:65], s[6:7], 0, v[162:163]
	s_ashr_i32 s11, s10, 31
	v_lshl_add_u64 v[64:65], s[10:11], 1, v[64:65]
	v_lshlrev_b32_e32 v66, 3, v129
	v_mov_b32_e32 v67, v128
	v_lshl_add_u64 v[64:65], v[64:65], 0, v[66:67]
	v_lshl_add_u64 v[64:65], v[64:65], 0, v[66:67]
	v_mul_f32_e32 v48, v48, v68
	v_mul_f32_e32 v49, v49, v68
	v_mul_f32_e32 v50, v50, v68
	v_mul_f32_e32 v51, v51, v68
	v_mul_f32_e32 v52, v52, v68
	v_mul_f32_e32 v53, v53, v68
	v_mul_f32_e32 v54, v54, v68
	v_mul_f32_e32 v55, v55, v68
	v_cvt_pk_bf16_f32 v48, v48, v49
	v_cvt_pk_bf16_f32 v49, v50, v51
	v_cvt_pk_bf16_f32 v50, v52, v53
	v_cvt_pk_bf16_f32 v51, v54, v55
	s_nop 1
	v_permlane32_swap_b32_e32 v48, v50
	v_permlane32_swap_b32_e32 v49, v51
	flat_store_dwordx4 v[64:65], v[48:51]
	v_mul_f32_e32 v56, v56, v68
	v_mul_f32_e32 v57, v57, v68
	v_mul_f32_e32 v58, v58, v68
	v_mul_f32_e32 v59, v59, v68
	v_mul_f32_e32 v60, v60, v68
	v_mul_f32_e32 v61, v61, v68
	v_mul_f32_e32 v62, v62, v68
	v_mul_f32_e32 v63, v63, v68
	v_cvt_pk_bf16_f32 v56, v56, v57
	v_cvt_pk_bf16_f32 v57, v58, v59
	v_cvt_pk_bf16_f32 v58, v60, v61
	v_cvt_pk_bf16_f32 v59, v62, v63
	s_nop 1
	v_permlane32_swap_b32_e32 v56, v58
	v_permlane32_swap_b32_e32 v57, v59
	flat_store_dwordx4 v[64:65], v[56:59] offset:32
	v_mul_f32_e32 v32, v32, v68
	v_mul_f32_e32 v33, v33, v68
	v_mul_f32_e32 v34, v34, v68
	v_mul_f32_e32 v35, v35, v68
	v_mul_f32_e32 v36, v36, v68
	v_mul_f32_e32 v37, v37, v68
	v_mul_f32_e32 v38, v38, v68
	v_mul_f32_e32 v39, v39, v68
	v_cvt_pk_bf16_f32 v32, v32, v33
	v_cvt_pk_bf16_f32 v33, v34, v35
	v_cvt_pk_bf16_f32 v34, v36, v37
	v_cvt_pk_bf16_f32 v35, v38, v39
	s_nop 1
	v_permlane32_swap_b32_e32 v32, v34
	v_permlane32_swap_b32_e32 v33, v35
	flat_store_dwordx4 v[64:65], v[32:35] offset:64
	v_mul_f32_e32 v40, v40, v68
	v_mul_f32_e32 v41, v41, v68
	v_mul_f32_e32 v42, v42, v68
	v_mul_f32_e32 v43, v43, v68
	v_mul_f32_e32 v44, v44, v68
	v_mul_f32_e32 v45, v45, v68
	v_mul_f32_e32 v46, v46, v68
	v_mul_f32_e32 v47, v47, v68
	v_cvt_pk_bf16_f32 v40, v40, v41
	v_cvt_pk_bf16_f32 v41, v42, v43
	v_cvt_pk_bf16_f32 v42, v44, v45
	v_cvt_pk_bf16_f32 v43, v46, v47
	s_nop 1
	v_permlane32_swap_b32_e32 v40, v42
	v_permlane32_swap_b32_e32 v41, v43
	flat_store_dwordx4 v[64:65], v[40:43] offset:96
	v_mul_f32_e32 v16, v16, v68
	v_mul_f32_e32 v17, v17, v68
	v_mul_f32_e32 v18, v18, v68
	v_mul_f32_e32 v19, v19, v68
	v_mul_f32_e32 v20, v20, v68
	v_mul_f32_e32 v21, v21, v68
	v_mul_f32_e32 v22, v22, v68
	v_mul_f32_e32 v23, v23, v68
	v_cvt_pk_bf16_f32 v16, v16, v17
	v_cvt_pk_bf16_f32 v17, v18, v19
	v_cvt_pk_bf16_f32 v18, v20, v21
	v_cvt_pk_bf16_f32 v19, v22, v23
	s_nop 1
	v_permlane32_swap_b32_e32 v16, v18
	v_permlane32_swap_b32_e32 v17, v19
	flat_store_dwordx4 v[64:65], v[16:19] offset:128
	v_mul_f32_e32 v24, v24, v68
	v_mul_f32_e32 v25, v25, v68
	v_mul_f32_e32 v26, v26, v68
	v_mul_f32_e32 v27, v27, v68
	v_mul_f32_e32 v28, v28, v68
	v_mul_f32_e32 v29, v29, v68
	v_mul_f32_e32 v30, v30, v68
	v_mul_f32_e32 v31, v31, v68
	v_cvt_pk_bf16_f32 v24, v24, v25
	v_cvt_pk_bf16_f32 v25, v26, v27
	v_cvt_pk_bf16_f32 v26, v28, v29
	v_cvt_pk_bf16_f32 v27, v30, v31
	s_nop 1
	v_permlane32_swap_b32_e32 v24, v26
	v_permlane32_swap_b32_e32 v25, v27
	flat_store_dwordx4 v[64:65], v[24:27] offset:160
	v_mul_f32_e32 v0, v0, v68
	v_mul_f32_e32 v1, v1, v68
	v_mul_f32_e32 v2, v2, v68
	v_mul_f32_e32 v3, v3, v68
	v_mul_f32_e32 v4, v4, v68
	v_mul_f32_e32 v5, v5, v68
	v_mul_f32_e32 v6, v6, v68
	v_mul_f32_e32 v7, v7, v68
	v_cvt_pk_bf16_f32 v0, v0, v1
	v_cvt_pk_bf16_f32 v1, v2, v3
	v_cvt_pk_bf16_f32 v2, v4, v5
	v_cvt_pk_bf16_f32 v3, v6, v7
	s_nop 1
	v_permlane32_swap_b32_e32 v0, v2
	v_permlane32_swap_b32_e32 v1, v3
	flat_store_dwordx4 v[64:65], v[0:3] offset:192
	v_mul_f32_e32 v8, v8, v68
	v_mul_f32_e32 v9, v9, v68
	v_mul_f32_e32 v10, v10, v68
	v_mul_f32_e32 v11, v11, v68
	v_mul_f32_e32 v12, v12, v68
	v_mul_f32_e32 v13, v13, v68
	v_mul_f32_e32 v14, v14, v68
	v_mul_f32_e32 v15, v15, v68
	v_cvt_pk_bf16_f32 v8, v8, v9
	v_cvt_pk_bf16_f32 v9, v10, v11
	v_cvt_pk_bf16_f32 v10, v12, v13
	v_cvt_pk_bf16_f32 v11, v14, v15
	s_nop 1
	v_permlane32_swap_b32_e32 v8, v10
	v_permlane32_swap_b32_e32 v9, v11
	flat_store_dwordx4 v[64:65], v[8:11] offset:224
	v_readlane_b32 s6, v254, 0
	s_nop 1
	s_add_i32 s19, s19, s6
	v_readlane_b32 s6, v255, 22
	s_nop 1
	s_add_i32 s18, s18, s6
	s_cmpk_gt_i32 s19, 0x3ff
	v_readlane_b32 s7, v254, 1
	s_cbranch_scc0 .LBB0_1708
